# C mixer: epilogue act stores paired into dwordx4 via permlane32_swap; mid-PV skip/rescale compares moved into MFMA gaps (SALU-only test exposed)
# baseline (speedup 1.0000x reference)
; #define LAS __attribute__((address_space(3)))
; __device__ __forceinline__ void attn_C_item(const bf16_t* P, bf16_t* act_c, int S, int seqbase, int q0, int h, float lam, float oml, const float* subln_g, LAS char* lds, int tid, int w, int lane) {
;     ...
;     auto fin = [&](const bool first) __attribute__((always_inline)) {
;             { auto rr = __builtin_amdgcn_permlane32_swap(__float_as_uint(rm), __float_as_uint(rm), false, false); rm = fmaxf(__uint_as_float(rr[0]), __uint_as_float(rr[1])); }
;             pvalid = first || !__all(rm < -150.0f);
;             if (pvalid) {
;                 if (first || __any(rm > 8.0f)) {
;                     const float dl = first ? rm : fmaxf(rm, 0.0f); m += dl;
;                     if (!first) { const float alpha = __builtin_amdgcn_exp2f(-dl); l *= alpha;
; #pragma unroll
;                     for (int db = 0; db < 4; ++db) o[db] = o[db] * alpha; }
; #pragma unroll
;                     for (int rg = 0; rg < 16; ++rg) { s0[rg] -= dl; s1[rg] -= dl; negm[rg] = -m; }
;                 }
;                 float ps0 = 0.f, ps1 = 0.f;
; #pragma unroll
;                 for (int rg = 0; rg < 16; ++rg) { s0[rg] = __builtin_amdgcn_exp2f(s0[rg]); s1[rg] = __builtin_amdgcn_exp2f(s1[rg]); ps0 += s0[rg]; ps1 += s1[rg]; }
;                 l += ps0 + ps1;
; #pragma unroll
;                 for (int st = 0; st < 2; ++st) {
;                     u32x4 wa, wb;
;                     wa.x = cvtpk(s0[8 * st + 0], s0[8 * st + 1]); wa.y = cvtpk(s0[8 * st + 2], s0[8 * st + 3]); wa.z = cvtpk(s0[8 * st + 4], s0[8 * st + 5]); wa.w = cvtpk(s0[8 * st + 6], s0[8 * st + 7]);
;                     wb.x = cvtpk(s1[8 * st + 0], s1[8 * st + 1]); wb.y = cvtpk(s1[8 * st + 2], s1[8 * st + 3]); wb.z = cvtpk(s1[8 * st + 4], s1[8 * st + 5]); wb.w = cvtpk(s1[8 * st + 6], s1[8 * st + 7]);
;                     pf[st] = __builtin_bit_cast(bf16x8, wa); pf[2 + st] = __builtin_bit_cast(bf16x8, wb);
;                 }
;             }
;     };
;     auto pv_bm = [&](const LAS char* bufp, const int T) __attribute__((always_inline)) {
;             const LAS char* vt = bufp + C_V + troff;
;             s16x4 vlo[2][4], vhi[2][4];
;     ...
;             __builtin_amdgcn_sched_barrier(0);
;             PV_RD(0, 0); PV_RD(1, 1);
;             C_BIASMAX(T);
;             PV_MM(0, 0); PV_RD(2, 0); PV_MM(1, 1); PV_RD(3, 1); PV_MM(2, 0); PV_MM(3, 1);
.Lc_pv:
	s_and_b32 s12, s17, 0x18000
	v_add_u32_e32 v185, s12, v248
	ds_read_b64_tr_b16 v[94:95], v185 offset:16384
	ds_read_b64_tr_b16 v[96:97], v185 offset:16896
	ds_read_b64_tr_b16 v[208:209], v185 offset:20480
	ds_read_b64_tr_b16 v[210:211], v185 offset:20992
	ds_read_b64_tr_b16 v[82:83], v185 offset:24576
	ds_read_b64_tr_b16 v[84:85], v185 offset:25088
	ds_read_b64_tr_b16 v[100:101], v185 offset:28672
	ds_read_b64_tr_b16 v[102:103], v185 offset:29184
	ds_read_b64_tr_b16 v[86:87], v185 offset:17408
	ds_read_b64_tr_b16 v[88:89], v185 offset:17920
	ds_read_b64_tr_b16 v[108:109], v185 offset:21504
	ds_read_b64_tr_b16 v[110:111], v185 offset:22016
	ds_read_b64_tr_b16 v[104:105], v185 offset:25600
	ds_read_b64_tr_b16 v[106:107], v185 offset:26112
	ds_read_b64_tr_b16 v[90:91], v185 offset:29696
	ds_read_b64_tr_b16 v[92:93], v185 offset:30208
	s_waitcnt lgkmcnt(14)
	v_mfma_f32_32x32x16_bf16 v[48:63], v[94:97], v[172:175], v[48:63]
	v_max_f32_e32 v183, v128, v129
	v_max_f32_e32 v207, v112, v113
	v_max3_f32 v183, v183, v130, v131
	v_max3_f32 v207, v207, v114, v115
	v_max3_f32 v183, v183, v132, v133
	v_max3_f32 v207, v207, v116, v117
	s_waitcnt lgkmcnt(12)
	v_mfma_f32_32x32x16_bf16 v[32:47], v[208:211], v[172:175], v[32:47]
	v_max3_f32 v183, v183, v134, v135
	v_max3_f32 v207, v207, v118, v119
	v_max3_f32 v183, v183, v136, v137
	v_max3_f32 v207, v207, v120, v121
	v_max3_f32 v183, v183, v138, v139
	v_max3_f32 v207, v207, v122, v123
	s_waitcnt lgkmcnt(10)
	v_mfma_f32_32x32x16_bf16 v[16:31], v[82:85], v[172:175], v[16:31]
	v_max3_f32 v183, v183, v140, v141
	v_max3_f32 v207, v207, v124, v125
	v_max3_f32 v183, v183, v142, v143
	v_max3_f32 v207, v207, v126, v127
	v_max_f32_e32 v65, v183, v207
	v_mov_b32_e32 v183, v65
	s_waitcnt lgkmcnt(8)
	v_mfma_f32_32x32x16_bf16 v[0:15], v[100:103], v[172:175], v[0:15]
	v_permlane32_swap_b32_e32 v65, v183
	s_mov_b32 s12, 0xc3160000
	s_mov_b32 s13, 0x41000000
	v_max_f32_e32 v65, v65, v183
	s_nop 0
	v_cmp_gt_f32_e64 s[22:23], s12, v65
	v_cmp_lt_f32_e32 vcc, s13, v65
	ds_read_b64_tr_b16 v[66:67], v185 offset:18432
	ds_read_b64_tr_b16 v[68:69], v185 offset:18944
	ds_read_b64_tr_b16 v[70:71], v185 offset:22528
	ds_read_b64_tr_b16 v[72:73], v185 offset:23040
	ds_read_b64_tr_b16 v[208:209], v185 offset:26624
	ds_read_b64_tr_b16 v[210:211], v185 offset:27136
	ds_read_b64_tr_b16 v[212:213], v185 offset:30720
	ds_read_b64_tr_b16 v[214:215], v185 offset:31232
	s_cmp_lg_u64 s[22:23], exec
	s_cselect_b64 s[18:19], -1, 0
	s_cmp_eq_u64 s[22:23], exec
	s_cbranch_scc1 .Lc_pvB_skip
	s_cbranch_vccnz .Lc_pvB_resc
	s_waitcnt lgkmcnt(14)
	v_mfma_f32_32x32x16_bf16 v[48:63], v[86:89], v[168:171], v[48:63]
	v_exp_f32_e32 v128, v128
	v_exp_f32_e32 v129, v129
	s_waitcnt lgkmcnt(12)
	v_mfma_f32_32x32x16_bf16 v[32:47], v[108:111], v[168:171], v[32:47]
	v_exp_f32_e32 v130, v130
	v_exp_f32_e32 v131, v131
	v_pk_add_f32 v[82:83], v[128:129], 0 op_sel_hi:[1,0]
	s_waitcnt lgkmcnt(10)
	v_mfma_f32_32x32x16_bf16 v[16:31], v[104:107], v[168:171], v[16:31]
	v_exp_f32_e32 v132, v132
	v_exp_f32_e32 v133, v133
	v_pk_add_f32 v[82:83], v[130:131], v[82:83]
	v_cvt_pk_bf16_f32 v172, v128, v129
	s_waitcnt lgkmcnt(8)
	v_mfma_f32_32x32x16_bf16 v[0:15], v[90:93], v[168:171], v[0:15]
	v_exp_f32_e32 v134, v134
	v_exp_f32_e32 v135, v135
	v_pk_add_f32 v[82:83], v[132:133], v[82:83]
	v_cvt_pk_bf16_f32 v173, v130, v131
	ds_read_b64_tr_b16 v[74:75], v185 offset:19456
	ds_read_b64_tr_b16 v[76:77], v185 offset:19968
	ds_read_b64_tr_b16 v[78:79], v185 offset:23552
	ds_read_b64_tr_b16 v[80:81], v185 offset:24064
	ds_read_b64_tr_b16 v[94:95], v185 offset:27648
	ds_read_b64_tr_b16 v[96:97], v185 offset:28160
	ds_read_b64_tr_b16 v[216:217], v185 offset:31744
	ds_read_b64_tr_b16 v[218:219], v185 offset:32256
	s_waitcnt lgkmcnt(14)
	v_mfma_f32_32x32x16_bf16 v[48:63], v[66:69], v[160:163], v[48:63]
	v_exp_f32_e32 v136, v136
	v_exp_f32_e32 v137, v137
	v_pk_add_f32 v[82:83], v[134:135], v[82:83]
	v_cvt_pk_bf16_f32 v174, v132, v133
	s_waitcnt lgkmcnt(12)
	v_mfma_f32_32x32x16_bf16 v[32:47], v[70:73], v[160:163], v[32:47]
	v_exp_f32_e32 v138, v138
	v_exp_f32_e32 v139, v139
	v_pk_add_f32 v[82:83], v[136:137], v[82:83]
	v_cvt_pk_bf16_f32 v175, v134, v135
	s_waitcnt lgkmcnt(10)
	v_mfma_f32_32x32x16_bf16 v[16:31], v[208:211], v[160:163], v[16:31]
	v_exp_f32_e32 v140, v140
	v_exp_f32_e32 v141, v141
	v_pk_add_f32 v[82:83], v[138:139], v[82:83]
	v_cvt_pk_bf16_f32 v168, v136, v137
	s_waitcnt lgkmcnt(8)
	v_mfma_f32_32x32x16_bf16 v[0:15], v[212:215], v[160:163], v[0:15]
	v_exp_f32_e32 v142, v142
	v_exp_f32_e32 v143, v143
	v_pk_add_f32 v[82:83], v[140:141], v[82:83]
	v_cvt_pk_bf16_f32 v169, v138, v139
	s_waitcnt lgkmcnt(6)
	v_mfma_f32_32x32x16_bf16 v[48:63], v[74:77], v[164:167], v[48:63]
	v_exp_f32_e32 v112, v112
	v_exp_f32_e32 v113, v113
	v_pk_add_f32 v[82:83], v[142:143], v[82:83]
	v_cvt_pk_bf16_f32 v170, v140, v141
	s_waitcnt lgkmcnt(4)
	v_mfma_f32_32x32x16_bf16 v[32:47], v[78:81], v[164:167], v[32:47]
	v_exp_f32_e32 v114, v114
	v_exp_f32_e32 v115, v115
	v_pk_add_f32 v[82:83], v[112:113], v[82:83]
	v_cvt_pk_bf16_f32 v171, v142, v143
	s_waitcnt lgkmcnt(2)
	v_mfma_f32_32x32x16_bf16 v[16:31], v[94:97], v[164:167], v[16:31]
	v_exp_f32_e32 v116, v116
	v_exp_f32_e32 v117, v117
	v_pk_add_f32 v[82:83], v[114:115], v[82:83]
	v_cvt_pk_bf16_f32 v160, v112, v113
	s_waitcnt lgkmcnt(0)
	v_mfma_f32_32x32x16_bf16 v[0:15], v[216:219], v[164:167], v[0:15]
	v_exp_f32_e32 v118, v118
	v_exp_f32_e32 v119, v119
	v_pk_add_f32 v[82:83], v[116:117], v[82:83]
	v_cvt_pk_bf16_f32 v161, v114, v115
	v_exp_f32_e32 v120, v120
	v_exp_f32_e32 v121, v121
	v_pk_add_f32 v[82:83], v[118:119], v[82:83]
	v_cvt_pk_bf16_f32 v162, v116, v117
	v_exp_f32_e32 v122, v122
	v_exp_f32_e32 v123, v123
	v_pk_add_f32 v[82:83], v[120:121], v[82:83]
	v_cvt_pk_bf16_f32 v163, v118, v119
	v_exp_f32_e32 v124, v124
	v_exp_f32_e32 v125, v125
	v_pk_add_f32 v[82:83], v[122:123], v[82:83]
	v_cvt_pk_bf16_f32 v164, v120, v121
	v_exp_f32_e32 v126, v126
	v_exp_f32_e32 v127, v127
	v_pk_add_f32 v[82:83], v[124:125], v[82:83]
	v_cvt_pk_bf16_f32 v165, v122, v123
	v_pk_add_f32 v[82:83], v[126:127], v[82:83]
	v_cvt_pk_bf16_f32 v166, v124, v125
	v_cvt_pk_bf16_f32 v167, v126, v127
	v_add_f32_e32 v82, v82, v83
	s_nop 0
	v_add_f32_e32 v205, v205, v82
	s_branch .LBB0_199

; #define LAS __attribute__((address_space(3)))
; __device__ __forceinline__ void attn_C_item(const bf16_t* P, bf16_t* act_c, int S, int seqbase, int q0, int h, float lam, float oml, const float* subln_g, LAS char* lds, int tid, int w, int lane) {
;     ...
;     l += __shfl_xor(l, 32);
;     const float inv = 1.0f / l;
;     LAS float* xch = (LAS float*)lds + (size_t)(w & 3) * 4096 + lane;
;     if (map == 1) {
; #pragma unroll
;         for (int db = 0; db < 4; ++db)
; #pragma unroll
;             for (int i = 0; i < 16; ++i) xch[(db * 16 + i) * 64] = o[db][i] * inv;
;     }
;     __syncthreads();
;     if (map == 0) {
;         float ss = 0.f;
; #pragma unroll
;         for (int db = 0; db < 4; ++db)
; #pragma unroll
;             for (int i = 0; i < 16; ++i) { const float d = o[db][i] * inv - lam * xch[(db * 16 + i) * 64]; o[db][i] = d; ss += d * d; }
;         ss += __shfl_xor(ss, 32);
;         const float rn = rsqrtf(ss * (1.0f / 128.0f) + RMS_EPS) * oml;
;         const int tok = seqbase + qrow + r;
;         const bf16_t* gate = P + PB(GC + h * 128) + (size_t)tok * 64;
;         bf16_t* dst = act_c + (size_t)tok * 512 + h * 128;
; #pragma unroll
;         for (int dh = 0; dh < 2; ++dh) {
;         u32x2 gwv[2][4]; f32x4 sgv[2][4];
; #pragma unroll
;         for (int db = 0; db < 2; ++db)
; #pragma unroll
;             for (int g4 = 0; g4 < 4; ++g4) { gwv[db][g4] = *(const u32x2*)(gate + (size_t)dh * MC * 64 + 32 * db + 8 * g4 + 4 * hh); sgv[db][g4] = *(const f32x4*)(subln_g + 32 * (2 * dh + db) + 8 * g4 + 4 * hh); }
.LBB0_219:
	s_andn2_b64 vcc, exec, s[42:43]
	s_waitcnt lgkmcnt(0)
	s_barrier
	s_cbranch_vccnz .LBB0_196
	ds_read2st64_b32 v[144:145], v247 offset1:1
	ds_read2st64_b32 v[146:147], v247 offset0:2 offset1:3
	ds_read2st64_b32 v[164:165], v247 offset0:4 offset1:5
	ds_read2st64_b32 v[168:169], v247 offset0:6 offset1:7
	ds_read2st64_b32 v[174:175], v247 offset0:8 offset1:9
	ds_read2st64_b32 v[190:191], v247 offset0:10 offset1:11
	ds_read2st64_b32 v[160:161], v247 offset0:12 offset1:13
	ds_read2st64_b32 v[162:163], v247 offset0:14 offset1:15
	ds_read2st64_b32 v[148:149], v247 offset0:16 offset1:17
	ds_read2st64_b32 v[150:151], v247 offset0:18 offset1:19
	ds_read2st64_b32 v[140:141], v247 offset0:20 offset1:21
	ds_read2st64_b32 v[142:143], v247 offset0:22 offset1:23
	ds_read2st64_b32 v[136:137], v247 offset0:24 offset1:25
	ds_read2st64_b32 v[138:139], v247 offset0:26 offset1:27
	ds_read2st64_b32 v[132:133], v247 offset0:28 offset1:29
	ds_read2st64_b32 v[134:135], v247 offset0:30 offset1:31
	ds_read2st64_b32 v[128:129], v247 offset0:32 offset1:33
	ds_read2st64_b32 v[130:131], v247 offset0:34 offset1:35
	ds_read2st64_b32 v[122:123], v247 offset0:36 offset1:37
	ds_read2st64_b32 v[126:127], v247 offset0:38 offset1:39
	ds_read2st64_b32 v[118:119], v247 offset0:40 offset1:41
	ds_read2st64_b32 v[120:121], v247 offset0:42 offset1:43
	ds_read2st64_b32 v[114:115], v247 offset0:44 offset1:45
	ds_read2st64_b32 v[116:117], v247 offset0:46 offset1:47
	ds_read2st64_b32 v[110:111], v247 offset0:48 offset1:49
	ds_read2st64_b32 v[112:113], v247 offset0:50 offset1:51
	ds_read2st64_b32 v[106:107], v247 offset0:52 offset1:53
	ds_read2st64_b32 v[108:109], v247 offset0:54 offset1:55
	ds_read2st64_b32 v[102:103], v247 offset0:56 offset1:57
	ds_read2st64_b32 v[104:105], v247 offset0:58 offset1:59
	ds_read2st64_b32 v[64:65], v247 offset0:60 offset1:61
	s_lshl_b32 s12, s48, 1
	s_mov_b32 s13, s16
	v_lshlrev_b32_e32 v172, 1, v178
	v_mov_b32_e32 v173, v193
	s_waitcnt lgkmcnt(0)
	v_pk_mul_f32 v[64:65], v[176:177], v[64:65]
	v_pk_mul_f32 v[144:145], v[176:177], v[144:145]
	v_pk_fma_f32 v[94:95], v[12:13], v[96:97], v[64:65] op_sel_hi:[1,0,1] neg_lo:[0,0,1] neg_hi:[0,0,1]
	ds_read2st64_b32 v[12:13], v247 offset0:62 offset1:63
	v_pk_mul_f32 v[146:147], v[176:177], v[146:147]
	v_pk_fma_f32 v[144:145], v[48:49], v[96:97], v[144:145] op_sel_hi:[1,0,1] neg_lo:[0,0,1] neg_hi:[0,0,1]
	v_pk_fma_f32 v[50:51], v[50:51], v[96:97], v[146:147] op_sel_hi:[1,0,1] neg_lo:[0,0,1] neg_hi:[0,0,1]
	v_pk_mul_f32 v[164:165], v[176:177], v[164:165]
	s_waitcnt lgkmcnt(0)
	v_pk_mul_f32 v[12:13], v[176:177], v[12:13]
	v_pk_mul_f32 v[168:169], v[176:177], v[168:169]
	v_pk_fma_f32 v[92:93], v[14:15], v[96:97], v[12:13] op_sel_hi:[1,0,1] neg_lo:[0,0,1] neg_hi:[0,0,1]
	v_lshlrev_b64 v[14:15], 10, v[186:187]
	v_lshl_add_u64 v[12:13], v[188:189], 1, s[60:61]
	v_lshl_add_u64 v[14:15], s[4:5], 0, v[14:15]
	v_lshl_add_u64 v[170:171], v[14:15], 0, s[12:13]
	v_lshl_add_u64 v[124:125], v[12:13], 0, v[172:173]
	s_mov_b64 s[12:13], 0xf800000
	v_lshl_add_u64 v[64:65], v[124:125], 0, s[12:13]
	s_mov_b32 s12, 0xf800000
	v_add_co_u32_e32 v12, vcc, s12, v124
	v_pk_mul_f32 v[174:175], v[176:177], v[174:175]
	s_nop 0
	v_addc_co_u32_e32 v13, vcc, 0, v125, vcc
	global_load_dwordx2 v[156:157], v[12:13], off
	s_nop 0
	global_load_dwordx4 v[12:15], v[180:181], off
	global_load_dwordx2 v[200:201], v[64:65], off offset:16
	global_load_dwordx4 v[88:91], v[180:181], off offset:32
	global_load_dwordx2 v[188:189], v[64:65], off offset:32
	global_load_dwordx4 v[84:87], v[180:181], off offset:64
	global_load_dwordx2 v[204:205], v[64:65], off offset:48
	global_load_dwordx4 v[80:83], v[180:181], off offset:96
	global_load_dwordx2 v[202:203], v[64:65], off offset:64
	global_load_dwordx4 v[76:79], v[180:181], off offset:128
	global_load_dwordx2 v[186:187], v[64:65], off offset:80
	global_load_dwordx4 v[72:75], v[180:181], off offset:160
	global_load_dwordx2 v[166:167], v[64:65], off offset:96
	global_load_dwordx4 v[68:71], v[180:181], off offset:192
	global_load_dwordx2 v[158:159], v[64:65], off offset:112
	s_nop 0
	global_load_dwordx4 v[64:67], v[180:181], off offset:224
	v_pk_mul_f32 v[190:191], v[176:177], v[190:191]
	v_pk_mul_f32 v[160:161], v[176:177], v[160:161]
	v_pk_mul_f32 v[162:163], v[176:177], v[162:163]
	v_pk_mul_f32 v[154:155], v[144:145], v[144:145]
	v_pk_mul_f32 v[152:153], v[50:51], v[50:51]
	v_pk_mul_f32 v[98:99], v[94:95], v[94:95]
	v_pk_mul_f32 v[100:101], v[92:93], v[92:93]
	s_mov_b32 s12, 0xfa00000
	s_waitcnt vmcnt(15)
	v_lshlrev_b32_e32 v48, 16, v156
	v_mul_f32_e32 v97, 0xbfb8aa3b, v48
	v_exp_f32_e32 v97, v97
	v_and_b32_e32 v49, 0xffff0000, v156
	v_add_f32_e32 v97, 1.0, v97
	v_rcp_f32_e32 v146, v97
	v_mul_f32_e32 v97, 0xbfb8aa3b, v49
	v_exp_f32_e32 v97, v97
	s_nop 0
	v_add_f32_e32 v97, 1.0, v97
	v_rcp_f32_e32 v147, v97
	s_nop 0
	v_pk_mul_f32 v[146:147], v[146:147], v[48:49]
	v_lshlrev_b32_e32 v48, 16, v157
	v_mul_f32_e32 v97, 0xbfb8aa3b, v48
	v_exp_f32_e32 v97, v97
	v_and_b32_e32 v49, 0xffff0000, v157
	v_add_f32_e32 v97, 1.0, v97
	v_rcp_f32_e32 v156, v97
	v_mul_f32_e32 v97, 0xbfb8aa3b, v49
	v_exp_f32_e32 v97, v97
	s_nop 0
	v_add_f32_e32 v97, 1.0, v97
	v_pk_fma_f32 v[52:53], v[52:53], v[96:97], v[164:165] op_sel_hi:[1,0,1] neg_lo:[0,0,1] neg_hi:[0,0,1]
	s_waitcnt vmcnt(13)
; __device__ __forceinline__ unsigned cvtpk(float lo, float hi) { f32x2 v = {lo, hi}; bf16x2_t b = __builtin_convertvector(v, bf16x2_t); return __builtin_bit_cast(unsigned, b); }
; __device__ __forceinline__ float bflo(unsigned w) { return __uint_as_float(w << 16); }
; __device__ __forceinline__ float bfhi(unsigned w) { return __uint_as_float(w & 0xffff0000u); }
; __device__ __forceinline__ float silu_(float x) { return x * __builtin_amdgcn_rcpf(1.0f + __builtin_amdgcn_exp2f(-x * LOG2E)); }
; __device__ __forceinline__ void attn_C_item(const bf16_t* P, bf16_t* act_c, int S, int seqbase, int q0, int h, float lam, float oml, const float* subln_g, LAS char* lds, int tid, int w, int lane) {
;     ...
;             for (int i = 0; i < 16; ++i) { const float d = o[db][i] * inv - lam * xch[(db * 16 + i) * 64]; o[db][i] = d; ss += d * d; }
;         ss += __shfl_xor(ss, 32);
;         const float rn = rsqrtf(ss * (1.0f / 128.0f) + RMS_EPS) * oml;
;         const int tok = seqbase + qrow + r;
;         const bf16_t* gate = P + PB(GC + h * 128) + (size_t)tok * 64;
;         bf16_t* dst = act_c + (size_t)tok * 512 + h * 128;
; #pragma unroll
;         for (int dh = 0; dh < 2; ++dh) {
;         u32x2 gwv[2][4]; f32x4 sgv[2][4];
; #pragma unroll
;         for (int db = 0; db < 2; ++db)
; #pragma unroll
;             for (int g4 = 0; g4 < 4; ++g4) { gwv[db][g4] = *(const u32x2*)(gate + (size_t)dh * MC * 64 + 32 * db + 8 * g4 + 4 * hh); sgv[db][g4] = *(const f32x4*)(subln_g + 32 * (2 * dh + db) + 8 * g4 + 4 * hh); }
;         asm volatile("" ::: "memory");
; #pragma unroll
;         for (int dbl = 0; dbl < 2; ++dbl)
; #pragma unroll
;             for (int g4 = 0; g4 < 4; ++g4) { const int db = 2 * dh + dbl; const int dv = 32 * db + 8 * g4 + 4 * hh;
;                 const u32x2 gw = gwv[dbl][g4]; const f32x4 sg = sgv[dbl][g4];
;                 u32x2 wv; wv.x = cvtpk(o[db][4 * g4 + 0] * rn * sg.x * silu_(bflo(gw.x)), o[db][4 * g4 + 1] * rn * sg.y * silu_(bfhi(gw.x)));
	v_lshlrev_b32_e32 v164, 16, v200
	v_rcp_f32_e32 v157, v97
	v_pk_fma_f32 v[54:55], v[54:55], v[96:97], v[168:169] op_sel_hi:[1,0,1] neg_lo:[0,0,1] neg_hi:[0,0,1]
	v_mul_f32_e32 v97, 0xbfb8aa3b, v164
	v_exp_f32_e32 v97, v97
	v_and_b32_e32 v165, 0xffff0000, v200
	v_pk_mul_f32 v[156:157], v[156:157], v[48:49]
	v_lshl_add_u64 v[48:49], v[170:171], 0, v[172:173]
	v_add_f32_e32 v97, 1.0, v97
	v_rcp_f32_e32 v168, v97
	v_mul_f32_e32 v97, 0xbfb8aa3b, v165
	v_exp_f32_e32 v97, v97
	v_pk_mul_f32 v[172:173], v[52:53], v[52:53]
	v_pk_mul_f32 v[170:171], v[54:55], v[54:55]
	v_add_f32_e32 v97, 1.0, v97
	v_rcp_f32_e32 v169, v97
	s_nop 0
	v_pk_mul_f32 v[164:165], v[168:169], v[164:165]
	v_lshlrev_b32_e32 v168, 16, v201
	v_mul_f32_e32 v97, 0xbfb8aa3b, v168
	v_exp_f32_e32 v97, v97
	v_and_b32_e32 v169, 0xffff0000, v201
	v_add_f32_e32 v97, 1.0, v97
	v_rcp_f32_e32 v200, v97
	v_mul_f32_e32 v97, 0xbfb8aa3b, v169
	v_exp_f32_e32 v97, v97
	s_nop 0
	v_add_f32_e32 v97, 1.0, v97
	v_pk_fma_f32 v[56:57], v[56:57], v[96:97], v[174:175] op_sel_hi:[1,0,1] neg_lo:[0,0,1] neg_hi:[0,0,1]
	s_waitcnt vmcnt(11)
	v_lshlrev_b32_e32 v174, 16, v188
	v_rcp_f32_e32 v201, v97
	v_pk_fma_f32 v[58:59], v[58:59], v[96:97], v[190:191] op_sel_hi:[1,0,1] neg_lo:[0,0,1] neg_hi:[0,0,1]
	v_mul_f32_e32 v97, 0xbfb8aa3b, v174
	v_exp_f32_e32 v97, v97
	v_and_b32_e32 v175, 0xffff0000, v188
	v_lshlrev_b32_e32 v188, 16, v189
	v_and_b32_e32 v189, 0xffff0000, v189
	v_add_f32_e32 v97, 1.0, v97
	v_rcp_f32_e32 v206, v97
	v_mul_f32_e32 v97, 0xbfb8aa3b, v175
	v_exp_f32_e32 v97, v97
	v_pk_mul_f32 v[168:169], v[200:201], v[168:169]
	v_pk_mul_f32 v[200:201], v[56:57], v[56:57]
	v_pk_mul_f32 v[190:191], v[58:59], v[58:59]
	v_add_f32_e32 v97, 1.0, v97
	v_rcp_f32_e32 v207, v97
	v_mul_f32_e32 v97, 0xbfb8aa3b, v188
	v_exp_f32_e32 v97, v97
	v_pk_mul_f32 v[174:175], v[206:207], v[174:175]
	v_add_f32_e32 v97, 1.0, v97
	v_rcp_f32_e32 v206, v97
	v_mul_f32_e32 v97, 0xbfb8aa3b, v189
	v_exp_f32_e32 v97, v97
	s_nop 0
	v_add_f32_e32 v97, 1.0, v97
	v_pk_fma_f32 v[160:161], v[60:61], v[96:97], v[160:161] op_sel_hi:[1,0,1] neg_lo:[0,0,1] neg_hi:[0,0,1]
	s_waitcnt vmcnt(9)
	v_lshlrev_b32_e32 v60, 16, v204
	v_rcp_f32_e32 v207, v97
	v_pk_fma_f32 v[62:63], v[62:63], v[96:97], v[162:163] op_sel_hi:[1,0,1] neg_lo:[0,0,1] neg_hi:[0,0,1]
	v_mul_f32_e32 v97, 0xbfb8aa3b, v60
	v_exp_f32_e32 v97, v97
	v_and_b32_e32 v61, 0xffff0000, v204
	v_pk_mul_f32 v[208:209], v[160:161], v[160:161]
	v_pk_mul_f32 v[188:189], v[206:207], v[188:189]
	v_add_f32_e32 v97, 1.0, v97
	v_rcp_f32_e32 v162, v97
	v_mul_f32_e32 v97, 0xbfb8aa3b, v61
	v_exp_f32_e32 v97, v97
	v_pk_mul_f32 v[206:207], v[62:63], v[62:63]
	v_add_f32_e32 v97, 1.0, v97
	v_rcp_f32_e32 v163, v97
	s_nop 0
	v_pk_mul_f32 v[162:163], v[162:163], v[60:61]
	v_lshlrev_b32_e32 v60, 16, v205
	v_mul_f32_e32 v97, 0xbfb8aa3b, v60
	v_exp_f32_e32 v97, v97
	v_and_b32_e32 v61, 0xffff0000, v205
	v_add_f32_e32 v97, 1.0, v97
	v_rcp_f32_e32 v204, v97
	v_mul_f32_e32 v97, 0xbfb8aa3b, v61
	v_exp_f32_e32 v97, v97
	s_nop 0
	v_add_f32_e32 v97, 1.0, v97
	v_rcp_f32_e32 v205, v97
	s_nop 0
	v_pk_mul_f32 v[204:205], v[204:205], v[60:61]
	v_pk_mul_f32 v[60:61], v[176:177], v[150:151]
	s_nop 0
	v_pk_fma_f32 v[34:35], v[34:35], v[96:97], v[60:61] op_sel_hi:[1,0,1] neg_lo:[0,0,1] neg_hi:[0,0,1]
	v_pk_mul_f32 v[60:61], v[176:177], v[148:149]
	v_pk_mul_f32 v[210:211], v[34:35], v[34:35]
	v_pk_fma_f32 v[148:149], v[32:33], v[96:97], v[60:61] op_sel_hi:[1,0,1] neg_lo:[0,0,1] neg_hi:[0,0,1]
	s_waitcnt vmcnt(7)
	v_lshlrev_b32_e32 v32, 16, v202
	v_and_b32_e32 v33, 0xffff0000, v202
	v_mul_f32_e32 v60, 0xbfb8aa3b, v32
	v_mul_f32_e32 v61, 0xbfb8aa3b, v33
	v_exp_f32_e32 v60, v60
	v_exp_f32_e32 v61, v61
	v_pk_mul_f32 v[212:213], v[148:149], v[148:149]
	v_add_f32_e32 v60, 1.0, v60
	v_add_f32_e32 v61, 1.0, v61
	v_rcp_f32_e32 v60, v60
	v_rcp_f32_e32 v61, v61
	s_nop 0
	v_pk_mul_f32 v[150:151], v[60:61], v[32:33]
	v_lshlrev_b32_e32 v32, 16, v203
	v_and_b32_e32 v33, 0xffff0000, v203
	v_mul_f32_e32 v60, 0xbfb8aa3b, v32
	v_mul_f32_e32 v61, 0xbfb8aa3b, v33
	v_exp_f32_e32 v60, v60
	v_exp_f32_e32 v61, v61
	v_add_f32_e32 v60, 1.0, v60
	v_add_f32_e32 v61, 1.0, v61
	v_rcp_f32_e32 v60, v60
	v_rcp_f32_e32 v61, v61
	s_nop 0
	v_pk_mul_f32 v[202:203], v[60:61], v[32:33]
	v_pk_mul_f32 v[32:33], v[176:177], v[142:143]
	s_nop 0
	v_pk_fma_f32 v[142:143], v[38:39], v[96:97], v[32:33] op_sel_hi:[1,0,1] neg_lo:[0,0,1] neg_hi:[0,0,1]
	v_pk_mul_f32 v[32:33], v[176:177], v[140:141]
	v_pk_mul_f32 v[216:217], v[142:143], v[142:143]
	v_pk_fma_f32 v[140:141], v[36:37], v[96:97], v[32:33] op_sel_hi:[1,0,1] neg_lo:[0,0,1] neg_hi:[0,0,1]
	s_waitcnt vmcnt(5)
	v_lshlrev_b32_e32 v32, 16, v186
	v_and_b32_e32 v33, 0xffff0000, v186
	v_mul_f32_e32 v36, 0xbfb8aa3b, v32
	v_mul_f32_e32 v37, 0xbfb8aa3b, v33
	v_exp_f32_e32 v36, v36
	v_exp_f32_e32 v37, v37
	v_pk_mul_f32 v[218:219], v[140:141], v[140:141]
	v_add_f32_e32 v36, 1.0, v36
	v_add_f32_e32 v37, 1.0, v37
	v_rcp_f32_e32 v36, v36
	v_rcp_f32_e32 v37, v37
	s_nop 0
	v_pk_mul_f32 v[214:215], v[36:37], v[32:33]
	v_lshlrev_b32_e32 v32, 16, v187
	v_and_b32_e32 v33, 0xffff0000, v187
	v_mul_f32_e32 v36, 0xbfb8aa3b, v32
	v_mul_f32_e32 v37, 0xbfb8aa3b, v33
	v_exp_f32_e32 v36, v36
	v_exp_f32_e32 v37, v37
	v_add_f32_e32 v36, 1.0, v36
	v_add_f32_e32 v37, 1.0, v37
	v_rcp_f32_e32 v36, v36
	v_rcp_f32_e32 v37, v37
	s_nop 0
	v_pk_mul_f32 v[186:187], v[36:37], v[32:33]
	v_pk_mul_f32 v[32:33], v[176:177], v[138:139]
	s_nop 0
	v_pk_fma_f32 v[138:139], v[42:43], v[96:97], v[32:33] op_sel_hi:[1,0,1] neg_lo:[0,0,1] neg_hi:[0,0,1]
	v_pk_mul_f32 v[32:33], v[176:177], v[136:137]
	v_pk_mul_f32 v[220:221], v[138:139], v[138:139]
	v_pk_fma_f32 v[40:41], v[40:41], v[96:97], v[32:33] op_sel_hi:[1,0,1] neg_lo:[0,0,1] neg_hi:[0,0,1]
	s_waitcnt vmcnt(3)
; __device__ __forceinline__ unsigned cvtpk(float lo, float hi) { f32x2 v = {lo, hi}; bf16x2_t b = __builtin_convertvector(v, bf16x2_t); return __builtin_bit_cast(unsigned, b); }
; __device__ __forceinline__ float bflo(unsigned w) { return __uint_as_float(w << 16); }
; __device__ __forceinline__ float bfhi(unsigned w) { return __uint_as_float(w & 0xffff0000u); }
; __device__ __forceinline__ float silu_(float x) { return x * __builtin_amdgcn_rcpf(1.0f + __builtin_amdgcn_exp2f(-x * LOG2E)); }
; __device__ __forceinline__ void attn_C_item(const bf16_t* P, bf16_t* act_c, int S, int seqbase, int q0, int h, float lam, float oml, const float* subln_g, LAS char* lds, int tid, int w, int lane) {
;     ...
;             for (int i = 0; i < 16; ++i) { const float d = o[db][i] * inv - lam * xch[(db * 16 + i) * 64]; o[db][i] = d; ss += d * d; }
;         ss += __shfl_xor(ss, 32);
;         const float rn = rsqrtf(ss * (1.0f / 128.0f) + RMS_EPS) * oml;
;         const int tok = seqbase + qrow + r;
;         const bf16_t* gate = P + PB(GC + h * 128) + (size_t)tok * 64;
;         bf16_t* dst = act_c + (size_t)tok * 512 + h * 128;
; #pragma unroll
;         for (int dh = 0; dh < 2; ++dh) {
;         u32x2 gwv[2][4]; f32x4 sgv[2][4];
; #pragma unroll
;         for (int db = 0; db < 2; ++db)
; #pragma unroll
;             for (int g4 = 0; g4 < 4; ++g4) { gwv[db][g4] = *(const u32x2*)(gate + (size_t)dh * MC * 64 + 32 * db + 8 * g4 + 4 * hh); sgv[db][g4] = *(const f32x4*)(subln_g + 32 * (2 * dh + db) + 8 * g4 + 4 * hh); }
;         asm volatile("" ::: "memory");
; #pragma unroll
;         for (int dbl = 0; dbl < 2; ++dbl)
; #pragma unroll
;             for (int g4 = 0; g4 < 4; ++g4) { const int db = 2 * dh + dbl; const int dv = 32 * db + 8 * g4 + 4 * hh;
;                 const u32x2 gw = gwv[dbl][g4]; const f32x4 sg = sgv[dbl][g4];
;                 u32x2 wv; wv.x = cvtpk(o[db][4 * g4 + 0] * rn * sg.x * silu_(bflo(gw.x)), o[db][4 * g4 + 1] * rn * sg.y * silu_(bfhi(gw.x)));
	v_lshlrev_b32_e32 v32, 16, v166
	v_and_b32_e32 v33, 0xffff0000, v166
	v_mul_f32_e32 v36, 0xbfb8aa3b, v32
	v_mul_f32_e32 v37, 0xbfb8aa3b, v33
	v_exp_f32_e32 v36, v36
	v_exp_f32_e32 v37, v37
	v_pk_mul_f32 v[222:223], v[40:41], v[40:41]
	v_add_f32_e32 v36, 1.0, v36
	v_add_f32_e32 v37, 1.0, v37
	v_rcp_f32_e32 v36, v36
	v_rcp_f32_e32 v37, v37
	s_nop 0
	v_pk_mul_f32 v[136:137], v[36:37], v[32:33]
	v_lshlrev_b32_e32 v32, 16, v167
	v_and_b32_e32 v33, 0xffff0000, v167
	v_mul_f32_e32 v36, 0xbfb8aa3b, v32
	v_mul_f32_e32 v37, 0xbfb8aa3b, v33
	v_exp_f32_e32 v36, v36
	v_exp_f32_e32 v37, v37
	v_add_f32_e32 v36, 1.0, v36
	v_add_f32_e32 v37, 1.0, v37
	v_rcp_f32_e32 v36, v36
	v_rcp_f32_e32 v37, v37
	s_nop 0
	v_pk_mul_f32 v[166:167], v[36:37], v[32:33]
	v_pk_mul_f32 v[32:33], v[176:177], v[134:135]
	s_nop 0
	v_pk_fma_f32 v[46:47], v[46:47], v[96:97], v[32:33] op_sel_hi:[1,0,1] neg_lo:[0,0,1] neg_hi:[0,0,1]
	v_pk_mul_f32 v[32:33], v[176:177], v[132:133]
	v_pk_mul_f32 v[250:251], v[46:47], v[46:47]
	v_pk_fma_f32 v[132:133], v[44:45], v[96:97], v[32:33] op_sel_hi:[1,0,1] neg_lo:[0,0,1] neg_hi:[0,0,1]
	s_waitcnt vmcnt(1)
	v_lshlrev_b32_e32 v32, 16, v158
	v_and_b32_e32 v33, 0xffff0000, v158
	v_mul_f32_e32 v36, 0xbfb8aa3b, v32
	v_mul_f32_e32 v37, 0xbfb8aa3b, v33
	v_exp_f32_e32 v36, v36
	v_exp_f32_e32 v37, v37
	v_pk_mul_f32 v[252:253], v[132:133], v[132:133]
	v_add_f32_e32 v36, 1.0, v36
	v_add_f32_e32 v37, 1.0, v37
	v_rcp_f32_e32 v36, v36
	v_rcp_f32_e32 v37, v37
	s_nop 0
	v_pk_mul_f32 v[134:135], v[36:37], v[32:33]
	v_lshlrev_b32_e32 v32, 16, v159
	v_and_b32_e32 v33, 0xffff0000, v159
	v_mul_f32_e32 v36, 0xbfb8aa3b, v32
	v_mul_f32_e32 v37, 0xbfb8aa3b, v33
	v_exp_f32_e32 v36, v36
	v_exp_f32_e32 v37, v37
	v_add_f32_e32 v36, 1.0, v36
	v_add_f32_e32 v37, 1.0, v37
	v_rcp_f32_e32 v36, v36
	v_rcp_f32_e32 v37, v37
	s_nop 0
	v_pk_mul_f32 v[158:159], v[36:37], v[32:33]
	v_pk_mul_f32 v[32:33], v[176:177], v[130:131]
	s_nop 0
	v_pk_fma_f32 v[130:131], v[18:19], v[96:97], v[32:33] op_sel_hi:[1,0,1] neg_lo:[0,0,1] neg_hi:[0,0,1]
	v_pk_mul_f32 v[32:33], v[176:177], v[128:129]
	v_pk_mul_f32 v[18:19], v[130:131], v[130:131]
	v_pk_fma_f32 v[128:129], v[16:17], v[96:97], v[32:33] op_sel_hi:[1,0,1] neg_lo:[0,0,1] neg_hi:[0,0,1]
	v_pk_mul_f32 v[32:33], v[176:177], v[126:127]
	v_pk_mul_f32 v[16:17], v[128:129], v[128:129]
	v_pk_fma_f32 v[126:127], v[22:23], v[96:97], v[32:33] op_sel_hi:[1,0,1] neg_lo:[0,0,1] neg_hi:[0,0,1]
	v_pk_mul_f32 v[32:33], v[176:177], v[122:123]
	v_pk_mul_f32 v[22:23], v[126:127], v[126:127]
	v_pk_fma_f32 v[122:123], v[20:21], v[96:97], v[32:33] op_sel_hi:[1,0,1] neg_lo:[0,0,1] neg_hi:[0,0,1]
	v_pk_mul_f32 v[32:33], v[176:177], v[120:121]
	v_pk_mul_f32 v[20:21], v[122:123], v[122:123]
	v_pk_fma_f32 v[120:121], v[26:27], v[96:97], v[32:33] op_sel_hi:[1,0,1] neg_lo:[0,0,1] neg_hi:[0,0,1]
	v_pk_mul_f32 v[32:33], v[176:177], v[118:119]
	v_pk_mul_f32 v[26:27], v[120:121], v[120:121]
	v_pk_fma_f32 v[118:119], v[24:25], v[96:97], v[32:33] op_sel_hi:[1,0,1] neg_lo:[0,0,1] neg_hi:[0,0,1]
	v_pk_mul_f32 v[32:33], v[176:177], v[116:117]
	v_pk_mul_f32 v[24:25], v[118:119], v[118:119]
	v_pk_fma_f32 v[60:61], v[30:31], v[96:97], v[32:33] op_sel_hi:[1,0,1] neg_lo:[0,0,1] neg_hi:[0,0,1]
	v_pk_mul_f32 v[30:31], v[176:177], v[114:115]
	v_pk_mul_f32 v[32:33], v[176:177], v[102:103]
	v_pk_fma_f32 v[114:115], v[28:29], v[96:97], v[30:31] op_sel_hi:[1,0,1] neg_lo:[0,0,1] neg_hi:[0,0,1]
	v_pk_mul_f32 v[30:31], v[176:177], v[112:113]
	v_pk_fma_f32 v[32:33], v[8:9], v[96:97], v[32:33] op_sel_hi:[1,0,1] neg_lo:[0,0,1] neg_hi:[0,0,1]
	v_pk_fma_f32 v[42:43], v[2:3], v[96:97], v[30:31] op_sel_hi:[1,0,1] neg_lo:[0,0,1] neg_hi:[0,0,1]
	v_pk_mul_f32 v[30:31], v[176:177], v[110:111]
	v_pk_mul_f32 v[28:29], v[114:115], v[114:115]
	v_pk_fma_f32 v[44:45], v[0:1], v[96:97], v[30:31] op_sel_hi:[1,0,1] neg_lo:[0,0,1] neg_hi:[0,0,1]
	v_pk_mul_f32 v[30:31], v[176:177], v[108:109]
	v_pk_mul_f32 v[116:117], v[60:61], v[60:61]
	v_pk_fma_f32 v[36:37], v[6:7], v[96:97], v[30:31] op_sel_hi:[1,0,1] neg_lo:[0,0,1] neg_hi:[0,0,1]
	v_pk_mul_f32 v[30:31], v[176:177], v[106:107]
	v_pk_mul_f32 v[0:1], v[44:45], v[44:45]
	v_pk_fma_f32 v[38:39], v[4:5], v[96:97], v[30:31] op_sel_hi:[1,0,1] neg_lo:[0,0,1] neg_hi:[0,0,1]
	v_pk_mul_f32 v[30:31], v[176:177], v[104:105]
	v_pk_mul_f32 v[2:3], v[42:43], v[42:43]
	v_pk_fma_f32 v[30:31], v[10:11], v[96:97], v[30:31] op_sel_hi:[1,0,1] neg_lo:[0,0,1] neg_hi:[0,0,1]
	v_add_f32_e32 v96, v154, v155
	v_add_f32_e32 v96, v96, v152
	v_add_f32_e32 v96, v96, v153
	v_add_f32_e32 v96, v96, v172
	v_add_f32_e32 v96, v96, v173
	v_add_f32_e32 v96, v96, v170
	v_add_f32_e32 v96, v96, v171
	v_add_f32_e32 v96, v96, v200
	v_add_f32_e32 v96, v96, v201
	v_add_f32_e32 v96, v96, v190
	v_add_f32_e32 v96, v96, v191
	v_add_f32_e32 v96, v96, v208
	v_add_f32_e32 v96, v96, v209
	v_add_f32_e32 v96, v96, v206
	v_add_f32_e32 v96, v96, v207
	v_add_f32_e32 v96, v96, v212
	v_add_f32_e32 v96, v96, v213
	v_add_f32_e32 v96, v96, v210
	v_add_f32_e32 v96, v96, v211
	v_add_f32_e32 v96, v96, v218
	v_add_f32_e32 v96, v96, v219
	v_add_f32_e32 v96, v96, v216
	v_add_f32_e32 v96, v96, v217
	v_add_f32_e32 v96, v96, v222
	v_add_f32_e32 v96, v96, v223
	v_add_f32_e32 v96, v96, v220
	v_add_f32_e32 v96, v96, v221
	v_add_f32_e32 v96, v96, v252
	v_add_f32_e32 v96, v96, v253
	v_add_f32_e32 v96, v96, v250
	v_add_f32_e32 v96, v96, v251
	v_add_f32_e32 v16, v96, v16
	v_add_f32_e32 v16, v16, v17
	v_add_f32_e32 v16, v16, v18
	v_add_f32_e32 v16, v16, v19
	v_add_f32_e32 v16, v16, v20
	v_add_f32_e32 v16, v16, v21
	v_add_f32_e32 v16, v16, v22
	v_add_f32_e32 v16, v16, v23
	v_add_f32_e32 v16, v16, v24
	v_add_f32_e32 v16, v16, v25
	v_add_f32_e32 v16, v16, v26
	v_add_f32_e32 v16, v16, v27
	v_add_f32_e32 v16, v16, v28
	v_add_f32_e32 v16, v16, v29
	v_add_f32_e32 v16, v16, v116
	v_add_f32_e32 v16, v16, v117
	v_add_f32_e32 v0, v16, v0
	v_add_f32_e32 v0, v0, v1
	v_add_f32_e32 v0, v0, v2
	v_pk_mul_f32 v[4:5], v[38:39], v[38:39]
	v_add_f32_e32 v0, v0, v3
	v_add_f32_e32 v0, v0, v4
	v_pk_mul_f32 v[6:7], v[36:37], v[36:37]
	v_add_f32_e32 v0, v0, v5
	v_add_f32_e32 v0, v0, v6
	v_pk_mul_f32 v[8:9], v[32:33], v[32:33]
	v_add_f32_e32 v0, v0, v7
	v_add_f32_e32 v0, v0, v8
	v_pk_mul_f32 v[10:11], v[30:31], v[30:31]
	v_add_f32_e32 v0, v0, v9
	v_add_f32_e32 v0, v0, v10
	v_add_f32_e32 v0, v0, v11
	v_add_f32_e32 v0, v0, v98
	v_add_f32_e32 v0, v0, v99
	v_add_f32_e32 v0, v0, v100
	v_add_f32_e32 v0, v0, v101
	ds_bpermute_b32 v1, v242, v0
	s_waitcnt lgkmcnt(0)
; __device__ __forceinline__ unsigned cvtpk(float lo, float hi) { f32x2 v = {lo, hi}; bf16x2_t b = __builtin_convertvector(v, bf16x2_t); return __builtin_bit_cast(unsigned, b); }
; __device__ __forceinline__ float bflo(unsigned w) { return __uint_as_float(w << 16); }
; __device__ __forceinline__ float bfhi(unsigned w) { return __uint_as_float(w & 0xffff0000u); }
; __device__ __forceinline__ float silu_(float x) { return x * __builtin_amdgcn_rcpf(1.0f + __builtin_amdgcn_exp2f(-x * LOG2E)); }
; __device__ __forceinline__ void attn_C_item(const bf16_t* P, bf16_t* act_c, int S, int seqbase, int q0, int h, float lam, float oml, const float* subln_g, LAS char* lds, int tid, int w, int lane) {
;     ...
;         const float rn = rsqrtf(ss * (1.0f / 128.0f) + RMS_EPS) * oml;
;         const int tok = seqbase + qrow + r;
;         const bf16_t* gate = P + PB(GC + h * 128) + (size_t)tok * 64;
;         bf16_t* dst = act_c + (size_t)tok * 512 + h * 128;
; #pragma unroll
;         for (int dh = 0; dh < 2; ++dh) {
;         u32x2 gwv[2][4]; f32x4 sgv[2][4];
; #pragma unroll
;         for (int db = 0; db < 2; ++db)
; #pragma unroll
;             for (int g4 = 0; g4 < 4; ++g4) { gwv[db][g4] = *(const u32x2*)(gate + (size_t)dh * MC * 64 + 32 * db + 8 * g4 + 4 * hh); sgv[db][g4] = *(const f32x4*)(subln_g + 32 * (2 * dh + db) + 8 * g4 + 4 * hh); }
;         asm volatile("" ::: "memory");
; #pragma unroll
;         for (int dbl = 0; dbl < 2; ++dbl)
; #pragma unroll
;             for (int g4 = 0; g4 < 4; ++g4) { const int db = 2 * dh + dbl; const int dv = 32 * db + 8 * g4 + 4 * hh;
;                 const u32x2 gw = gwv[dbl][g4]; const f32x4 sg = sgv[dbl][g4];
;                 u32x2 wv; wv.x = cvtpk(o[db][4 * g4 + 0] * rn * sg.x * silu_(bflo(gw.x)), o[db][4 * g4 + 1] * rn * sg.y * silu_(bfhi(gw.x)));
;                 wv.y = cvtpk(o[db][4 * g4 + 2] * rn * sg.z * silu_(bflo(gw.y)), o[db][4 * g4 + 3] * rn * sg.w * silu_(bfhi(gw.y)));
;                 *(u32x2*)(dst + dv) = wv; }
	v_add_f32_e32 v0, v0, v1
	v_fmamk_f32 v0, v0, 0x3c000000, v230
	v_cmp_gt_f32_e32 vcc, s37, v0
	v_mul_f32_e32 v1, 0x4b800000, v0
	s_nop 0
	v_cndmask_b32_e32 v0, v0, v1, vcc
	v_rsq_f32_e32 v0, v0
	s_nop 0
	v_mul_f32_e32 v1, 0x45800000, v0
	v_cndmask_b32_e32 v0, v0, v1, vcc
	v_mul_f32_e32 v28, v179, v0
	v_mbcnt_lo_u32_b32 v104, -1, 0
	v_mbcnt_hi_u32_b32 v104, -1, v104
	v_and_b32_e32 v104, 32, v104
	v_lshrrev_b32_e32 v104, 2, v104
	v_mov_b32_e32 v105, 0
	v_lshl_add_u64 v[106:107], v[48:49], 0, v[104:105]
	v_pk_mul_f32 v[0:1], v[144:145], v[28:29] op_sel_hi:[1,0]
	v_pk_mul_f32 v[2:3], v[50:51], v[28:29] op_sel_hi:[1,0]
	v_pk_mul_f32 v[0:1], v[12:13], v[0:1]
	v_pk_mul_f32 v[2:3], v[14:15], v[2:3]
	v_pk_mul_f32 v[0:1], v[146:147], v[0:1]
	v_pk_mul_f32 v[2:3], v[156:157], v[2:3]
	v_cvt_pk_bf16_f32 v96, v0, v1
	v_cvt_pk_bf16_f32 v97, v2, v3
	v_pk_mul_f32 v[0:1], v[52:53], v[28:29] op_sel_hi:[1,0]
	v_pk_mul_f32 v[2:3], v[54:55], v[28:29] op_sel_hi:[1,0]
	v_pk_mul_f32 v[0:1], v[88:89], v[0:1]
	v_pk_mul_f32 v[2:3], v[90:91], v[2:3]
	v_pk_mul_f32 v[0:1], v[164:165], v[0:1]
	v_pk_mul_f32 v[2:3], v[168:169], v[2:3]
	v_cvt_pk_bf16_f32 v98, v0, v1
	v_cvt_pk_bf16_f32 v99, v2, v3
	s_nop 1
	v_permlane32_swap_b32_e32 v96, v98
	v_permlane32_swap_b32_e32 v97, v99
	global_store_dwordx4 v[106:107], v[96:99], off
	v_pk_mul_f32 v[0:1], v[56:57], v[28:29] op_sel_hi:[1,0]
	v_pk_mul_f32 v[2:3], v[58:59], v[28:29] op_sel_hi:[1,0]
	v_pk_mul_f32 v[0:1], v[84:85], v[0:1]
	v_pk_mul_f32 v[2:3], v[86:87], v[2:3]
	v_pk_mul_f32 v[0:1], v[174:175], v[0:1]
	v_pk_mul_f32 v[2:3], v[188:189], v[2:3]
	v_cvt_pk_bf16_f32 v100, v0, v1
	v_cvt_pk_bf16_f32 v101, v2, v3
	v_pk_mul_f32 v[0:1], v[160:161], v[28:29] op_sel_hi:[1,0]
	v_pk_mul_f32 v[2:3], v[62:63], v[28:29] op_sel_hi:[1,0]
	v_pk_mul_f32 v[0:1], v[80:81], v[0:1]
	v_pk_mul_f32 v[2:3], v[82:83], v[2:3]
	v_pk_mul_f32 v[0:1], v[0:1], v[162:163]
	v_pk_mul_f32 v[2:3], v[2:3], v[204:205]
	v_cvt_pk_bf16_f32 v102, v0, v1
	v_cvt_pk_bf16_f32 v103, v2, v3
	s_nop 1
	v_permlane32_swap_b32_e32 v100, v102
	v_permlane32_swap_b32_e32 v101, v103
	global_store_dwordx4 v[106:107], v[100:103], off offset:32
	v_pk_mul_f32 v[0:1], v[148:149], v[28:29] op_sel_hi:[1,0]
	v_pk_mul_f32 v[2:3], v[34:35], v[28:29] op_sel_hi:[1,0]
	v_pk_mul_f32 v[0:1], v[76:77], v[0:1]
	v_pk_mul_f32 v[2:3], v[78:79], v[2:3]
	v_pk_mul_f32 v[0:1], v[0:1], v[150:151]
	v_pk_mul_f32 v[2:3], v[2:3], v[202:203]
	v_cvt_pk_bf16_f32 v96, v0, v1
	v_cvt_pk_bf16_f32 v97, v2, v3
	v_pk_mul_f32 v[0:1], v[140:141], v[28:29] op_sel_hi:[1,0]
	v_pk_mul_f32 v[2:3], v[142:143], v[28:29] op_sel_hi:[1,0]
	v_pk_mul_f32 v[0:1], v[72:73], v[0:1]
	v_pk_mul_f32 v[2:3], v[74:75], v[2:3]
	v_pk_mul_f32 v[0:1], v[0:1], v[214:215]
	v_pk_mul_f32 v[2:3], v[2:3], v[186:187]
	v_cvt_pk_bf16_f32 v98, v0, v1
	v_cvt_pk_bf16_f32 v99, v2, v3
	s_nop 1
	v_permlane32_swap_b32_e32 v96, v98
	v_permlane32_swap_b32_e32 v97, v99
	global_store_dwordx4 v[106:107], v[96:99], off offset:64
	v_pk_mul_f32 v[0:1], v[40:41], v[28:29] op_sel_hi:[1,0]
	v_pk_mul_f32 v[2:3], v[138:139], v[28:29] op_sel_hi:[1,0]
	v_pk_mul_f32 v[0:1], v[0:1], v[68:69]
	v_pk_mul_f32 v[2:3], v[2:3], v[70:71]
	v_pk_mul_f32 v[0:1], v[0:1], v[136:137]
	v_pk_mul_f32 v[2:3], v[2:3], v[166:167]
	v_cvt_pk_bf16_f32 v100, v0, v1
	v_cvt_pk_bf16_f32 v101, v2, v3
	v_pk_mul_f32 v[0:1], v[132:133], v[28:29] op_sel_hi:[1,0]
	v_pk_mul_f32 v[2:3], v[46:47], v[28:29] op_sel_hi:[1,0]
	s_waitcnt vmcnt(3)
	v_pk_mul_f32 v[0:1], v[0:1], v[64:65]
	v_pk_mul_f32 v[2:3], v[2:3], v[66:67]
	v_pk_mul_f32 v[0:1], v[0:1], v[134:135]
	v_pk_mul_f32 v[2:3], v[2:3], v[158:159]
	v_cvt_pk_bf16_f32 v102, v0, v1
	v_cvt_pk_bf16_f32 v103, v2, v3
	s_nop 1
	v_permlane32_swap_b32_e32 v100, v102
	v_permlane32_swap_b32_e32 v101, v103
	global_store_dwordx4 v[106:107], v[100:103], off offset:96
	v_add_co_u32_e32 v0, vcc, s12, v124
	s_nop 1
	v_addc_co_u32_e32 v1, vcc, 0, v125, vcc
	global_load_dwordx2 v[62:63], v[0:1], off
	global_load_dwordx4 v[56:59], v[180:181], off offset:256
	global_load_dwordx2 v[64:65], v[0:1], off offset:16
	global_load_dwordx4 v[24:27], v[180:181], off offset:288
	global_load_dwordx2 v[54:55], v[0:1], off offset:32
	global_load_dwordx4 v[20:23], v[180:181], off offset:320
	global_load_dwordx2 v[52:53], v[0:1], off offset:48
	global_load_dwordx4 v[16:19], v[180:181], off offset:352
	global_load_dwordx2 v[50:51], v[0:1], off offset:64
	global_load_dwordx4 v[12:15], v[180:181], off offset:384
	global_load_dwordx2 v[46:47], v[0:1], off offset:80
	global_load_dwordx4 v[8:11], v[180:181], off offset:416
	global_load_dwordx2 v[40:41], v[0:1], off offset:96
	global_load_dwordx4 v[4:7], v[180:181], off offset:448
	global_load_dwordx2 v[34:35], v[0:1], off offset:112
	s_nop 0
	global_load_dwordx4 v[0:3], v[180:181], off offset:480
	s_waitcnt vmcnt(15)
	v_lshlrev_b32_e32 v66, 16, v62
	v_mul_f32_e32 v29, 0xbfb8aa3b, v66
	v_exp_f32_e32 v29, v29
	v_and_b32_e32 v67, 0xffff0000, v62
	v_lshlrev_b32_e32 v62, 16, v63
	v_and_b32_e32 v63, 0xffff0000, v63
	v_add_f32_e32 v29, 1.0, v29
	v_rcp_f32_e32 v68, v29
	v_pk_mul_f32 v[70:71], v[128:129], v[28:29] op_sel_hi:[1,0]
	v_mul_f32_e32 v29, 0xbfb8aa3b, v67
	v_exp_f32_e32 v29, v29
	s_waitcnt vmcnt(14)
	v_pk_mul_f32 v[56:57], v[70:71], v[56:57]
	v_add_f32_e32 v29, 1.0, v29
	v_rcp_f32_e32 v69, v29
	v_mul_f32_e32 v29, 0xbfb8aa3b, v62
	v_exp_f32_e32 v29, v29
	v_pk_mul_f32 v[66:67], v[68:69], v[66:67]
	s_nop 0
	v_pk_mul_f32 v[56:57], v[56:57], v[66:67]
	v_add_f32_e32 v29, 1.0, v29
	v_rcp_f32_e32 v66, v29
	v_pk_mul_f32 v[68:69], v[130:131], v[28:29] op_sel_hi:[1,0]
	v_mul_f32_e32 v29, 0xbfb8aa3b, v63
	v_exp_f32_e32 v29, v29
	v_pk_mul_f32 v[58:59], v[68:69], v[58:59]
	v_cvt_pk_bf16_f32 v96, v56, v57
	v_add_f32_e32 v29, 1.0, v29
	v_rcp_f32_e32 v67, v29
	s_nop 0
	v_pk_mul_f32 v[62:63], v[66:67], v[62:63]
	s_nop 0
	v_pk_mul_f32 v[58:59], v[58:59], v[62:63]
	s_nop 0
	v_cvt_pk_bf16_f32 v97, v58, v59
	s_waitcnt vmcnt(13)
; __device__ __forceinline__ unsigned cvtpk(float lo, float hi) { f32x2 v = {lo, hi}; bf16x2_t b = __builtin_convertvector(v, bf16x2_t); return __builtin_bit_cast(unsigned, b); }
; __device__ __forceinline__ float bflo(unsigned w) { return __uint_as_float(w << 16); }
; __device__ __forceinline__ float bfhi(unsigned w) { return __uint_as_float(w & 0xffff0000u); }
; __device__ __forceinline__ float silu_(float x) { return x * __builtin_amdgcn_rcpf(1.0f + __builtin_amdgcn_exp2f(-x * LOG2E)); }
; __device__ __forceinline__ void attn_C_item(const bf16_t* P, bf16_t* act_c, int S, int seqbase, int q0, int h, float lam, float oml, const float* subln_g, LAS char* lds, int tid, int w, int lane) {
;     ...
;         for (int dh = 0; dh < 2; ++dh) {
;         u32x2 gwv[2][4]; f32x4 sgv[2][4];
; #pragma unroll
;         for (int db = 0; db < 2; ++db)
; #pragma unroll
;             for (int g4 = 0; g4 < 4; ++g4) { gwv[db][g4] = *(const u32x2*)(gate + (size_t)dh * MC * 64 + 32 * db + 8 * g4 + 4 * hh); sgv[db][g4] = *(const f32x4*)(subln_g + 32 * (2 * dh + db) + 8 * g4 + 4 * hh); }
;         asm volatile("" ::: "memory");
; #pragma unroll
;         for (int dbl = 0; dbl < 2; ++dbl)
; #pragma unroll
;             for (int g4 = 0; g4 < 4; ++g4) { const int db = 2 * dh + dbl; const int dv = 32 * db + 8 * g4 + 4 * hh;
;                 const u32x2 gw = gwv[dbl][g4]; const f32x4 sg = sgv[dbl][g4];
;                 u32x2 wv; wv.x = cvtpk(o[db][4 * g4 + 0] * rn * sg.x * silu_(bflo(gw.x)), o[db][4 * g4 + 1] * rn * sg.y * silu_(bfhi(gw.x)));
;                 wv.y = cvtpk(o[db][4 * g4 + 2] * rn * sg.z * silu_(bflo(gw.y)), o[db][4 * g4 + 3] * rn * sg.w * silu_(bfhi(gw.y)));
;                 *(u32x2*)(dst + dv) = wv; }
	v_lshlrev_b32_e32 v56, 16, v64
	v_mul_f32_e32 v29, 0xbfb8aa3b, v56
	v_exp_f32_e32 v29, v29
	v_and_b32_e32 v57, 0xffff0000, v64
	v_add_f32_e32 v29, 1.0, v29
	v_rcp_f32_e32 v58, v29
	v_pk_mul_f32 v[62:63], v[122:123], v[28:29] op_sel_hi:[1,0]
	v_mul_f32_e32 v29, 0xbfb8aa3b, v57
	v_exp_f32_e32 v29, v29
	s_waitcnt vmcnt(12)
	v_pk_mul_f32 v[24:25], v[62:63], v[24:25]
	v_add_f32_e32 v29, 1.0, v29
	v_rcp_f32_e32 v59, v29
	v_pk_mul_f32 v[62:63], v[126:127], v[28:29] op_sel_hi:[1,0]
	v_pk_mul_f32 v[56:57], v[58:59], v[56:57]
	s_nop 0
	v_pk_mul_f32 v[24:25], v[24:25], v[56:57]
	v_lshlrev_b32_e32 v56, 16, v65
	v_cvt_pk_bf16_f32 v98, v24, v25
	v_mul_f32_e32 v25, 0xbfb8aa3b, v56
	v_exp_f32_e32 v25, v25
	v_and_b32_e32 v57, 0xffff0000, v65
	v_pk_mul_f32 v[26:27], v[62:63], v[26:27]
	v_add_f32_e32 v25, 1.0, v25
	v_rcp_f32_e32 v58, v25
	v_mul_f32_e32 v25, 0xbfb8aa3b, v57
	v_exp_f32_e32 v25, v25
	s_nop 0
	v_add_f32_e32 v25, 1.0, v25
	v_rcp_f32_e32 v59, v25
	s_nop 0
	v_pk_mul_f32 v[56:57], v[58:59], v[56:57]
	s_nop 0
	v_pk_mul_f32 v[26:27], v[26:27], v[56:57]
	v_pk_mul_f32 v[56:57], v[118:119], v[28:29] op_sel_hi:[1,0]
	v_cvt_pk_bf16_f32 v99, v26, v27
	s_nop 1
	v_permlane32_swap_b32_e32 v96, v98
	v_permlane32_swap_b32_e32 v97, v99
	global_store_dwordx4 v[106:107], v[96:99], off offset:128
	s_waitcnt vmcnt(12)
	v_lshlrev_b32_e32 v24, 16, v54
	v_and_b32_e32 v25, 0xffff0000, v54
	v_mul_f32_e32 v26, 0xbfb8aa3b, v24
	v_mul_f32_e32 v27, 0xbfb8aa3b, v25
	v_exp_f32_e32 v26, v26
	v_exp_f32_e32 v27, v27
	s_waitcnt vmcnt(11)
	v_pk_mul_f32 v[20:21], v[56:57], v[20:21]
	v_add_f32_e32 v26, 1.0, v26
	v_add_f32_e32 v27, 1.0, v27
	v_rcp_f32_e32 v26, v26
	v_rcp_f32_e32 v27, v27
	s_nop 0
	v_pk_mul_f32 v[24:25], v[26:27], v[24:25]
	s_nop 0
	v_pk_mul_f32 v[20:21], v[20:21], v[24:25]
	v_lshlrev_b32_e32 v24, 16, v55
	v_cvt_pk_bf16_f32 v100, v20, v21
	v_mul_f32_e32 v21, 0xbfb8aa3b, v24
	v_exp_f32_e32 v21, v21
	v_and_b32_e32 v25, 0xffff0000, v55
	v_pk_mul_f32 v[54:55], v[120:121], v[28:29] op_sel_hi:[1,0]
	v_add_f32_e32 v21, 1.0, v21
	v_rcp_f32_e32 v26, v21
	v_mul_f32_e32 v21, 0xbfb8aa3b, v25
	v_exp_f32_e32 v21, v21
	v_pk_mul_f32 v[22:23], v[54:55], v[22:23]
	v_add_f32_e32 v21, 1.0, v21
	v_rcp_f32_e32 v27, v21
	s_nop 0
	v_pk_mul_f32 v[24:25], v[26:27], v[24:25]
	s_nop 0
	v_pk_mul_f32 v[22:23], v[22:23], v[24:25]
	v_pk_mul_f32 v[24:25], v[114:115], v[28:29] op_sel_hi:[1,0]
	v_cvt_pk_bf16_f32 v101, v22, v23
	s_waitcnt vmcnt(10)
	v_lshlrev_b32_e32 v20, 16, v52
	v_and_b32_e32 v21, 0xffff0000, v52
	v_mul_f32_e32 v22, 0xbfb8aa3b, v20
	v_mul_f32_e32 v23, 0xbfb8aa3b, v21
	v_exp_f32_e32 v22, v22
	v_exp_f32_e32 v23, v23
	s_waitcnt vmcnt(9)
	v_pk_mul_f32 v[16:17], v[24:25], v[16:17]
	v_pk_mul_f32 v[24:25], v[60:61], v[28:29] op_sel_hi:[1,0]
	v_add_f32_e32 v22, 1.0, v22
	v_add_f32_e32 v23, 1.0, v23
	v_rcp_f32_e32 v22, v22
	v_rcp_f32_e32 v23, v23
	v_pk_mul_f32 v[18:19], v[24:25], v[18:19]
	v_pk_mul_f32 v[20:21], v[22:23], v[20:21]
	s_nop 0
	v_pk_mul_f32 v[16:17], v[16:17], v[20:21]
	v_lshlrev_b32_e32 v20, 16, v53
	v_cvt_pk_bf16_f32 v102, v16, v17
	v_mul_f32_e32 v17, 0xbfb8aa3b, v20
	v_exp_f32_e32 v17, v17
	v_and_b32_e32 v21, 0xffff0000, v53
	v_add_f32_e32 v17, 1.0, v17
	v_rcp_f32_e32 v22, v17
	v_mul_f32_e32 v17, 0xbfb8aa3b, v21
	v_exp_f32_e32 v17, v17
	s_nop 0
	v_add_f32_e32 v17, 1.0, v17
	v_rcp_f32_e32 v23, v17
	s_nop 0
	v_pk_mul_f32 v[20:21], v[22:23], v[20:21]
	s_nop 0
	v_pk_mul_f32 v[18:19], v[18:19], v[20:21]
	v_pk_mul_f32 v[20:21], v[44:45], v[28:29] op_sel_hi:[1,0]
	v_cvt_pk_bf16_f32 v103, v18, v19
	s_nop 1
	v_permlane32_swap_b32_e32 v100, v102
	v_permlane32_swap_b32_e32 v101, v103
	global_store_dwordx4 v[106:107], v[100:103], off offset:160
	s_waitcnt vmcnt(9)
	v_lshlrev_b32_e32 v16, 16, v50
	v_and_b32_e32 v17, 0xffff0000, v50
	v_mul_f32_e32 v18, 0xbfb8aa3b, v16
	v_mul_f32_e32 v19, 0xbfb8aa3b, v17
	v_exp_f32_e32 v18, v18
	v_exp_f32_e32 v19, v19
	s_waitcnt vmcnt(8)
; __device__ __forceinline__ unsigned cvtpk(float lo, float hi) { f32x2 v = {lo, hi}; bf16x2_t b = __builtin_convertvector(v, bf16x2_t); return __builtin_bit_cast(unsigned, b); }
; __device__ __forceinline__ float bflo(unsigned w) { return __uint_as_float(w << 16); }
; __device__ __forceinline__ float bfhi(unsigned w) { return __uint_as_float(w & 0xffff0000u); }
; __device__ __forceinline__ float silu_(float x) { return x * __builtin_amdgcn_rcpf(1.0f + __builtin_amdgcn_exp2f(-x * LOG2E)); }
; __device__ __forceinline__ void attn_C_item(const bf16_t* P, bf16_t* act_c, int S, int seqbase, int q0, int h, float lam, float oml, const float* subln_g, LAS char* lds, int tid, int w, int lane) {
;     ...
;         for (int dh = 0; dh < 2; ++dh) {
;         u32x2 gwv[2][4]; f32x4 sgv[2][4];
; #pragma unroll
;         for (int db = 0; db < 2; ++db)
; #pragma unroll
;             for (int g4 = 0; g4 < 4; ++g4) { gwv[db][g4] = *(const u32x2*)(gate + (size_t)dh * MC * 64 + 32 * db + 8 * g4 + 4 * hh); sgv[db][g4] = *(const f32x4*)(subln_g + 32 * (2 * dh + db) + 8 * g4 + 4 * hh); }
;         asm volatile("" ::: "memory");
; #pragma unroll
;         for (int dbl = 0; dbl < 2; ++dbl)
; #pragma unroll
;             for (int g4 = 0; g4 < 4; ++g4) { const int db = 2 * dh + dbl; const int dv = 32 * db + 8 * g4 + 4 * hh;
;                 const u32x2 gw = gwv[dbl][g4]; const f32x4 sg = sgv[dbl][g4];
;                 u32x2 wv; wv.x = cvtpk(o[db][4 * g4 + 0] * rn * sg.x * silu_(bflo(gw.x)), o[db][4 * g4 + 1] * rn * sg.y * silu_(bfhi(gw.x)));
;                 wv.y = cvtpk(o[db][4 * g4 + 2] * rn * sg.z * silu_(bflo(gw.y)), o[db][4 * g4 + 3] * rn * sg.w * silu_(bfhi(gw.y)));
;                 *(u32x2*)(dst + dv) = wv; }
	v_pk_mul_f32 v[12:13], v[20:21], v[12:13]
	v_pk_mul_f32 v[20:21], v[42:43], v[28:29] op_sel_hi:[1,0]
	v_add_f32_e32 v18, 1.0, v18
	v_add_f32_e32 v19, 1.0, v19
	v_rcp_f32_e32 v18, v18
	v_rcp_f32_e32 v19, v19
	v_pk_mul_f32 v[14:15], v[20:21], v[14:15]
	v_pk_mul_f32 v[16:17], v[18:19], v[16:17]
	s_nop 0
	v_pk_mul_f32 v[12:13], v[12:13], v[16:17]
	v_lshlrev_b32_e32 v16, 16, v51
	v_cvt_pk_bf16_f32 v96, v12, v13
	v_mul_f32_e32 v13, 0xbfb8aa3b, v16
	v_exp_f32_e32 v13, v13
	v_and_b32_e32 v17, 0xffff0000, v51
	v_add_f32_e32 v13, 1.0, v13
	v_rcp_f32_e32 v18, v13
	v_mul_f32_e32 v13, 0xbfb8aa3b, v17
	v_exp_f32_e32 v13, v13
	s_nop 0
	v_add_f32_e32 v13, 1.0, v13
	v_rcp_f32_e32 v19, v13
	s_nop 0
	v_pk_mul_f32 v[16:17], v[18:19], v[16:17]
	s_nop 0
	v_pk_mul_f32 v[14:15], v[14:15], v[16:17]
	v_pk_mul_f32 v[16:17], v[38:39], v[28:29] op_sel_hi:[1,0]
	v_cvt_pk_bf16_f32 v97, v14, v15
	s_waitcnt vmcnt(7)
	v_lshlrev_b32_e32 v12, 16, v46
	v_and_b32_e32 v13, 0xffff0000, v46
	v_mul_f32_e32 v14, 0xbfb8aa3b, v12
	v_mul_f32_e32 v15, 0xbfb8aa3b, v13
	v_exp_f32_e32 v14, v14
	v_exp_f32_e32 v15, v15
	s_waitcnt vmcnt(6)
	v_pk_mul_f32 v[8:9], v[16:17], v[8:9]
	v_pk_mul_f32 v[16:17], v[36:37], v[28:29] op_sel_hi:[1,0]
	v_add_f32_e32 v14, 1.0, v14
	v_add_f32_e32 v15, 1.0, v15
	v_rcp_f32_e32 v14, v14
	v_rcp_f32_e32 v15, v15
	v_pk_mul_f32 v[10:11], v[16:17], v[10:11]
	v_pk_mul_f32 v[12:13], v[14:15], v[12:13]
	s_nop 0
	v_pk_mul_f32 v[8:9], v[8:9], v[12:13]
	v_lshlrev_b32_e32 v12, 16, v47
	v_cvt_pk_bf16_f32 v98, v8, v9
	v_mul_f32_e32 v9, 0xbfb8aa3b, v12
	v_exp_f32_e32 v9, v9
	v_and_b32_e32 v13, 0xffff0000, v47
	v_add_f32_e32 v9, 1.0, v9
	v_rcp_f32_e32 v14, v9
	v_mul_f32_e32 v9, 0xbfb8aa3b, v13
	v_exp_f32_e32 v9, v9
	s_nop 0
	v_add_f32_e32 v9, 1.0, v9
	v_rcp_f32_e32 v15, v9
	s_nop 0
	v_pk_mul_f32 v[12:13], v[14:15], v[12:13]
	s_nop 0
	v_pk_mul_f32 v[10:11], v[10:11], v[12:13]
	v_pk_mul_f32 v[12:13], v[32:33], v[28:29] op_sel_hi:[1,0]
	v_cvt_pk_bf16_f32 v99, v10, v11
	s_nop 1
	v_permlane32_swap_b32_e32 v96, v98
	v_permlane32_swap_b32_e32 v97, v99
	global_store_dwordx4 v[106:107], v[96:99], off offset:192
	s_waitcnt vmcnt(6)
	v_lshlrev_b32_e32 v8, 16, v40
	v_and_b32_e32 v9, 0xffff0000, v40
	v_mul_f32_e32 v10, 0xbfb8aa3b, v8
	v_mul_f32_e32 v11, 0xbfb8aa3b, v9
	v_exp_f32_e32 v10, v10
	v_exp_f32_e32 v11, v11
	s_waitcnt vmcnt(5)
	v_pk_mul_f32 v[4:5], v[12:13], v[4:5]
	v_pk_mul_f32 v[12:13], v[30:31], v[28:29] op_sel_hi:[1,0]
	v_add_f32_e32 v10, 1.0, v10
	v_add_f32_e32 v11, 1.0, v11
	v_rcp_f32_e32 v10, v10
	v_rcp_f32_e32 v11, v11
	v_pk_mul_f32 v[6:7], v[12:13], v[6:7]
	v_pk_mul_f32 v[8:9], v[10:11], v[8:9]
	s_nop 0
	v_pk_mul_f32 v[4:5], v[4:5], v[8:9]
	v_lshlrev_b32_e32 v8, 16, v41
	v_cvt_pk_bf16_f32 v100, v4, v5
	v_mul_f32_e32 v5, 0xbfb8aa3b, v8
	v_exp_f32_e32 v5, v5
	v_and_b32_e32 v9, 0xffff0000, v41
	v_add_f32_e32 v5, 1.0, v5
	v_rcp_f32_e32 v10, v5
	v_mul_f32_e32 v5, 0xbfb8aa3b, v9
	v_exp_f32_e32 v5, v5
	s_nop 0
	v_add_f32_e32 v5, 1.0, v5
	v_rcp_f32_e32 v11, v5
	s_nop 0
	v_pk_mul_f32 v[8:9], v[10:11], v[8:9]
	s_nop 0
	v_pk_mul_f32 v[6:7], v[6:7], v[8:9]
	v_pk_mul_f32 v[8:9], v[94:95], v[28:29] op_sel_hi:[1,0]
	v_cvt_pk_bf16_f32 v101, v6, v7
	s_waitcnt vmcnt(4)
	v_lshlrev_b32_e32 v4, 16, v34
	v_and_b32_e32 v5, 0xffff0000, v34
	v_mul_f32_e32 v6, 0xbfb8aa3b, v4
	v_mul_f32_e32 v7, 0xbfb8aa3b, v5
	v_exp_f32_e32 v6, v6
	v_exp_f32_e32 v7, v7
	s_waitcnt vmcnt(3)
	v_pk_mul_f32 v[0:1], v[8:9], v[0:1]
	v_pk_mul_f32 v[8:9], v[92:93], v[28:29] op_sel_hi:[1,0]
	v_add_f32_e32 v6, 1.0, v6
	v_add_f32_e32 v7, 1.0, v7
	v_rcp_f32_e32 v6, v6
	v_rcp_f32_e32 v7, v7
	v_pk_mul_f32 v[2:3], v[8:9], v[2:3]
	v_pk_mul_f32 v[4:5], v[6:7], v[4:5]
	s_nop 0
	v_pk_mul_f32 v[0:1], v[0:1], v[4:5]
	v_lshlrev_b32_e32 v4, 16, v35
	v_cvt_pk_bf16_f32 v102, v0, v1
	v_mul_f32_e32 v1, 0xbfb8aa3b, v4
	v_exp_f32_e32 v1, v1
	v_and_b32_e32 v5, 0xffff0000, v35
	v_add_f32_e32 v1, 1.0, v1
	v_rcp_f32_e32 v6, v1
	v_mul_f32_e32 v1, 0xbfb8aa3b, v5
	v_exp_f32_e32 v1, v1
	s_nop 0
	v_add_f32_e32 v1, 1.0, v1
	v_rcp_f32_e32 v7, v1
	s_nop 0
	v_pk_mul_f32 v[4:5], v[6:7], v[4:5]
	s_nop 0
	v_pk_mul_f32 v[2:3], v[2:3], v[4:5]
	s_nop 0
	v_cvt_pk_bf16_f32 v103, v2, v3
	s_nop 1
	v_permlane32_swap_b32_e32 v100, v102
	v_permlane32_swap_b32_e32 v101, v103
	global_store_dwordx4 v[106:107], v[100:103], off offset:224
	s_branch .LBB0_196
